# MLA loop: second-K-chunk tile load issued only by the waves that write it to LDS (exec-masked)
# baseline (speedup 1.0000x reference)
.Lmla_skipA:
	v_mfma_f32_32x32x16_bf16 v[96:111], v[222:225], v[152:155], v[80:95]
	ds_read_b128 v[222:225], v220 offset:64
	s_waitcnt vmcnt(0)
	ds_write_b128 v216, v[184:187]
	s_and_saveexec_b64 vcc, s[4:5]
	ds_write_b128 v217, v[180:183]
	s_mov_b64 exec, vcc
	ds_write2_b64 v219, v[176:177], v[178:179] offset0:128 offset1:130
	v_exp_f32_e32 v64, v64
	v_exp_f32_e32 v65, v65
	v_exp_f32_e32 v66, v66
	v_mfma_f32_32x32x16_bf16 v[80:95], v[226:229], v[152:155], v[80:95]
	ds_read_b128 v[226:229], v220 offset:6720
	v_exp_f32_e32 v67, v67
	v_exp_f32_e32 v68, v68
	v_exp_f32_e32 v69, v69
	v_exp_f32_e32 v70, v70
	v_exp_f32_e32 v71, v71
	s_waitcnt lgkmcnt(6)
	v_mfma_f32_32x32x16_bf16 v[96:111], v[230:233], v[156:159], v[96:111]
	ds_read_b128 v[230:233], v220 offset:96
	s_add_i32 s0, s9, 2
	s_min_u32 s0, s0, 0x7f
	s_mul_i32 s2, s0, 0x3000
	s_lshl_b32 s0, s0, 7
	v_lshl_add_u64 v[184:185], v[194:195], 0, s[2:3]
	v_lshl_add_u64 v[180:181], v[196:197], 0, s[2:3]
	v_lshl_add_u64 v[176:177], v[198:199], 0, s[0:1]
	global_load_dwordx4 v[184:187], v[184:185], off
	s_and_saveexec_b64 vcc, s[4:5]
	global_load_dwordx4 v[180:183], v[180:181], off
	s_mov_b64 exec, vcc
	global_load_dwordx4 v[176:179], v[176:177], off
	v_exp_f32_e32 v72, v72
	v_add_f32_e32 v203, v203, v64
	s_waitcnt lgkmcnt(6)
	v_mfma_f32_32x32x16_bf16 v[80:95], v[234:237], v[156:159], v[80:95]
	ds_read_b128 v[234:237], v220 offset:6752
	s_mov_b32 s2, 0x5800
	s_cmp_eq_u32 s10, 0
	s_cselect_b32 s2, 0xffff5000, s2
	v_add_u32_e32 v216, s2, v216
	v_add_u32_e32 v217, s2, v217
	v_add_u32_e32 v219, s2, v219
	s_mov_b32 s3, 0
	v_exp_f32_e32 v73, v73
	v_add_f32_e32 v203, v203, v65
	v_exp_f32_e32 v74, v74
	v_add_f32_e32 v203, v203, v66
	s_waitcnt lgkmcnt(6)
	v_mfma_f32_32x32x16_bf16 v[96:111], v[222:225], v[160:163], v[96:111]
	ds_read_b128 v[222:225], v220 offset:128
	v_exp_f32_e32 v75, v75
	v_add_f32_e32 v203, v203, v67
	v_exp_f32_e32 v76, v76
	v_add_f32_e32 v203, v203, v68
	v_exp_f32_e32 v77, v77
	v_add_f32_e32 v203, v203, v69
	s_waitcnt lgkmcnt(3)
	v_mfma_f32_32x32x16_bf16 v[80:95], v[226:229], v[160:163], v[80:95]
	ds_read_b128 v[226:229], v220 offset:6784
	v_exp_f32_e32 v78, v78
	v_add_f32_e32 v203, v203, v70
	v_exp_f32_e32 v79, v79
	v_add_f32_e32 v203, v203, v71
	v_cvt_pk_bf16_f32 v64, v64, v65
	v_cvt_pk_bf16_f32 v65, v66, v67
	v_cvt_pk_bf16_f32 v66, v68, v69
	v_cvt_pk_bf16_f32 v67, v70, v71
	s_waitcnt lgkmcnt(3)
	v_mfma_f32_32x32x16_bf16 v[96:111], v[230:233], v[164:167], v[96:111]
	ds_read_b128 v[230:233], v220 offset:160
	v_exp_f32_e32 v112, v112
	v_add_f32_e32 v203, v203, v72
	v_exp_f32_e32 v113, v113
	v_add_f32_e32 v203, v203, v73
	v_exp_f32_e32 v114, v114
	v_add_f32_e32 v203, v203, v74
	s_waitcnt lgkmcnt(3)
	v_mfma_f32_32x32x16_bf16 v[80:95], v[234:237], v[164:167], v[80:95]
	ds_read_b128 v[234:237], v220 offset:6816
	v_exp_f32_e32 v115, v115
	v_add_f32_e32 v203, v203, v75
	v_exp_f32_e32 v116, v116
	v_add_f32_e32 v203, v203, v76
	v_exp_f32_e32 v117, v117
	v_add_f32_e32 v203, v203, v77
	s_waitcnt lgkmcnt(3)
	v_mfma_f32_32x32x16_bf16 v[96:111], v[222:225], v[168:171], v[96:111]
	ds_read_b128 v[222:225], v221 offset:64
	v_exp_f32_e32 v118, v118
	v_add_f32_e32 v203, v203, v78
	v_exp_f32_e32 v119, v119
	v_add_f32_e32 v203, v203, v79
	v_cvt_pk_bf16_f32 v72, v72, v73
	v_cvt_pk_bf16_f32 v73, v74, v75
	v_cvt_pk_bf16_f32 v74, v76, v77
	v_cvt_pk_bf16_f32 v75, v78, v79
	s_waitcnt lgkmcnt(3)
	v_mfma_f32_32x32x16_bf16 v[80:95], v[226:229], v[168:171], v[80:95]
	ds_read_b128 v[226:229], v221 offset:4672
	s_mov_b32 s2, 0x5800
	s_cmp_eq_u32 s10, 2
	s_cselect_b32 s2, 0xffff5000, s2
	v_add_u32_e32 v220, s2, v220
	s_mov_b32 s3, 0
	v_exp_f32_e32 v120, v120
	v_add_f32_e32 v203, v203, v112
	v_exp_f32_e32 v121, v121
	v_add_f32_e32 v203, v203, v113
	v_exp_f32_e32 v122, v122
	v_add_f32_e32 v203, v203, v114
	s_waitcnt lgkmcnt(3)
	v_mfma_f32_32x32x16_bf16 v[96:111], v[230:233], v[172:175], v[96:111]
	ds_read_b128 v[230:233], v221 offset:96
	v_exp_f32_e32 v123, v123
	v_add_f32_e32 v203, v203, v115
	v_exp_f32_e32 v124, v124
	v_add_f32_e32 v203, v203, v116
	v_exp_f32_e32 v125, v125
	v_add_f32_e32 v203, v203, v117
	s_waitcnt lgkmcnt(3)
	v_mfma_f32_32x32x16_bf16 v[80:95], v[234:237], v[172:175], v[80:95]
	ds_read_b128 v[234:237], v221 offset:4704
	v_exp_f32_e32 v126, v126
	v_add_f32_e32 v203, v203, v118
	v_exp_f32_e32 v127, v127
	v_add_f32_e32 v203, v203, v119
	v_cvt_pk_bf16_f32 v112, v112, v113
	v_cvt_pk_bf16_f32 v113, v114, v115
	v_cvt_pk_bf16_f32 v114, v116, v117
	v_cvt_pk_bf16_f32 v115, v118, v119
	s_waitcnt lgkmcnt(3)
	v_mfma_f32_32x32x16_bf16 v[32:47], v[222:225], v[64:67], v[32:47]
	ds_read_b128 v[222:225], v221
	v_add_f32_e32 v203, v203, v120
	v_add_f32_e32 v203, v203, v121
	v_add_f32_e32 v203, v203, v122
	v_add_f32_e32 v203, v203, v123
	v_add_f32_e32 v203, v203, v124
	v_add_f32_e32 v203, v203, v125
	v_add_f32_e32 v203, v203, v126
	v_add_f32_e32 v203, v203, v127
	v_cvt_pk_bf16_f32 v120, v120, v121
	v_cvt_pk_bf16_f32 v121, v122, v123
	s_waitcnt lgkmcnt(3)
	v_mfma_f32_32x32x16_bf16 v[48:63], v[226:229], v[64:67], v[48:63]
	ds_read_b128 v[226:229], v221 offset:4608
	v_cvt_pk_bf16_f32 v122, v124, v125
	v_cvt_pk_bf16_f32 v123, v126, v127
	s_waitcnt lgkmcnt(3)
	v_mfma_f32_32x32x16_bf16 v[32:47], v[230:233], v[72:75], v[32:47]
	ds_read_b128 v[230:233], v221 offset:32
	v_max3_f32 v238, v96, v97, v98
	v_max3_f32 v238, v238, v99, v100
	v_max3_f32 v238, v238, v101, v102
	v_max3_f32 v238, v238, v103, v104
	s_waitcnt lgkmcnt(3)
	v_mfma_f32_32x32x16_bf16 v[48:63], v[234:237], v[72:75], v[48:63]
	ds_read_b128 v[234:237], v221 offset:4640
	v_max3_f32 v239, v80, v81, v82
	v_max3_f32 v238, v238, v105, v106
	v_max3_f32 v239, v239, v83, v84
	v_max3_f32 v238, v238, v107, v108
	v_max3_f32 v239, v239, v85, v86
	v_max3_f32 v238, v238, v109, v110
	v_max3_f32 v239, v239, v87, v88
	v_max_f32_e32 v238, v238, v111
	v_max3_f32 v239, v239, v89, v90
	v_max3_f32 v239, v239, v91, v92
	s_waitcnt lgkmcnt(3)
	v_mfma_f32_32x32x16_bf16 v[32:47], v[222:225], v[112:115], v[32:47]
	ds_read_b128 v[222:225], v220
	v_max3_f32 v239, v239, v93, v94
	v_max_f32_e32 v239, v239, v95
	v_max_f32_e32 v238, v238, v239
	ds_bpermute_b32 v188, v218, v238
	v_xor_b32_e32 v64, 0x80000000, v202
	v_mov_b32_e32 v65, v64
	v_mov_b32_e32 v66, v64
	v_mov_b32_e32 v67, v64
	v_mov_b32_e32 v68, v64
	v_mov_b32_e32 v69, v64
	v_mov_b32_e32 v70, v64
	s_waitcnt lgkmcnt(4)
	v_mfma_f32_32x32x16_bf16 v[48:63], v[226:229], v[112:115], v[48:63]
	ds_read_b128 v[226:229], v220 offset:6656
	v_mov_b32_e32 v71, v64
	v_mov_b32_e32 v72, v64
	v_mov_b32_e32 v73, v64
	v_mov_b32_e32 v74, v64
	v_mov_b32_e32 v75, v64
	v_mov_b32_e32 v76, v64
	v_mov_b32_e32 v77, v64
	v_mov_b32_e32 v78, v64
	v_mov_b32_e32 v79, v64
	s_waitcnt lgkmcnt(4)
	v_mfma_f32_32x32x16_bf16 v[32:47], v[230:233], v[120:123], v[32:47]
	ds_read_b128 v[230:233], v220 offset:32
	s_waitcnt lgkmcnt(2)
	v_max_f32_e32 v238, v238, v188
	v_cmp_lt_f32_e32 vcc, 0x41000000, v238
	s_cbranch_vccz .Lmla_skipB
	s_nop 15
	v_max_f32_e32 v238, 0, v238
	v_exp_f32_e64 v239, -v238
	v_add_f32_e32 v200, v200, v238
	s_nop 0
	v_mul_f32_e32 v201, v201, v239
	v_mul_f32_e32 v0, v0, v239
	v_mul_f32_e32 v1, v1, v239
	v_mul_f32_e32 v2, v2, v239
	v_mul_f32_e32 v3, v3, v239
	v_mul_f32_e32 v4, v4, v239
	v_mul_f32_e32 v5, v5, v239
	v_mul_f32_e32 v6, v6, v239
	v_mul_f32_e32 v7, v7, v239
	v_mul_f32_e32 v8, v8, v239
	v_mul_f32_e32 v9, v9, v239
	v_mul_f32_e32 v10, v10, v239
	v_mul_f32_e32 v11, v11, v239
	v_mul_f32_e32 v12, v12, v239
	v_mul_f32_e32 v13, v13, v239
	v_mul_f32_e32 v14, v14, v239
	v_mul_f32_e32 v15, v15, v239
	v_mul_f32_e32 v16, v16, v239
	v_mul_f32_e32 v17, v17, v239
	v_mul_f32_e32 v18, v18, v239
	v_mul_f32_e32 v19, v19, v239
	v_mul_f32_e32 v20, v20, v239
	v_mul_f32_e32 v21, v21, v239
	v_mul_f32_e32 v22, v22, v239
	v_mul_f32_e32 v23, v23, v239
	v_mul_f32_e32 v24, v24, v239
	v_mul_f32_e32 v25, v25, v239
	v_mul_f32_e32 v26, v26, v239
	v_mul_f32_e32 v27, v27, v239
	v_mul_f32_e32 v28, v28, v239
	v_mul_f32_e32 v29, v29, v239
	v_mul_f32_e32 v30, v30, v239
	v_mul_f32_e32 v31, v31, v239
	v_sub_f32_e32 v96, v96, v238
	v_sub_f32_e32 v97, v97, v238
	v_sub_f32_e32 v98, v98, v238
	v_sub_f32_e32 v99, v99, v238
	v_sub_f32_e32 v100, v100, v238
	v_sub_f32_e32 v101, v101, v238
	v_sub_f32_e32 v102, v102, v238
	v_sub_f32_e32 v103, v103, v238
	v_sub_f32_e32 v104, v104, v238
	v_sub_f32_e32 v105, v105, v238
	v_sub_f32_e32 v106, v106, v238
	v_sub_f32_e32 v107, v107, v238
	v_sub_f32_e32 v108, v108, v238
	v_sub_f32_e32 v109, v109, v238
	v_sub_f32_e32 v110, v110, v238
	v_sub_f32_e32 v111, v111, v238
	v_sub_f32_e32 v80, v80, v238
	v_sub_f32_e32 v81, v81, v238
	v_sub_f32_e32 v82, v82, v238
	v_sub_f32_e32 v83, v83, v238
	v_sub_f32_e32 v84, v84, v238
	v_sub_f32_e32 v85, v85, v238
	v_sub_f32_e32 v86, v86, v238
	v_sub_f32_e32 v87, v87, v238
	v_sub_f32_e32 v88, v88, v238
	v_sub_f32_e32 v89, v89, v238
	v_sub_f32_e32 v90, v90, v238
	v_sub_f32_e32 v91, v91, v238
	v_sub_f32_e32 v92, v92, v238
	v_sub_f32_e32 v93, v93, v238
	v_sub_f32_e32 v94, v94, v238
	v_sub_f32_e32 v95, v95, v238
